# workgroups without a tile in the MLA down-projection GEMM prefetch the q/kv up-projection weights into their XCD's L2
# speedup vs baseline: 1.0170x; 1.0014x over previous
.Lpf_idle:
	s_bfe_u32 s0, s97, 0x30003
	s_mul_i32 vcc_lo, s30, 0x120000
	s_mul_i32 vcc_hi, s0, 0x24000
	s_add_i32 vcc_lo, vcc_lo, vcc_hi
	s_add_i32 vcc_lo, vcc_lo, 0xe00000
	s_add_u32 s2, s58, vcc_lo
	s_addc_u32 s3, s59, 0
	v_lshlrev_b32_e32 v2, 4, v193
	global_load_dwordx4 v[4:7], v2, s[2:3]
	v_add_u32_e32 v2, 0x2000, v2
	global_load_dwordx4 v[4:7], v2, s[2:3]
	v_add_u32_e32 v2, 0x2000, v2
	global_load_dwordx4 v[4:7], v2, s[2:3]
	v_add_u32_e32 v2, 0x2000, v2
	global_load_dwordx4 v[4:7], v2, s[2:3]
	v_add_u32_e32 v2, 0x2000, v2
	global_load_dwordx4 v[4:7], v2, s[2:3]
	v_add_u32_e32 v2, 0x2000, v2
	global_load_dwordx4 v[4:7], v2, s[2:3]
	v_add_u32_e32 v2, 0x2000, v2
	global_load_dwordx4 v[4:7], v2, s[2:3]
	v_add_u32_e32 v2, 0x2000, v2
	global_load_dwordx4 v[4:7], v2, s[2:3]
	v_add_u32_e32 v2, 0x2000, v2
	global_load_dwordx4 v[4:7], v2, s[2:3]
	v_add_u32_e32 v2, 0x2000, v2
	global_load_dwordx4 v[4:7], v2, s[2:3]
	v_add_u32_e32 v2, 0x2000, v2
	global_load_dwordx4 v[4:7], v2, s[2:3]
	v_add_u32_e32 v2, 0x2000, v2
	global_load_dwordx4 v[4:7], v2, s[2:3]
	v_add_u32_e32 v2, 0x2000, v2
	global_load_dwordx4 v[4:7], v2, s[2:3]
	v_add_u32_e32 v2, 0x2000, v2
	global_load_dwordx4 v[4:7], v2, s[2:3]
	v_add_u32_e32 v2, 0x2000, v2
	global_load_dwordx4 v[4:7], v2, s[2:3]
	v_add_u32_e32 v2, 0x2000, v2
	global_load_dwordx4 v[4:7], v2, s[2:3]
	v_add_u32_e32 v2, 0x2000, v2
	global_load_dwordx4 v[4:7], v2, s[2:3]
	v_add_u32_e32 v2, 0x2000, v2
	global_load_dwordx4 v[4:7], v2, s[2:3]
	v_add_u32_e32 v2, 0x2000, v2
	s_mul_i32 vcc_lo, s30, 0x100000
	s_mul_i32 vcc_hi, s0, 0x20000
	s_add_i32 vcc_lo, vcc_lo, vcc_hi
	s_add_i32 vcc_lo, vcc_lo, 0x1040000
	s_add_u32 s2, s58, vcc_lo
	s_addc_u32 s3, s59, 0
	v_lshlrev_b32_e32 v2, 4, v193
	global_load_dwordx4 v[4:7], v2, s[2:3]
	v_add_u32_e32 v2, 0x2000, v2
	global_load_dwordx4 v[4:7], v2, s[2:3]
	v_add_u32_e32 v2, 0x2000, v2
	global_load_dwordx4 v[4:7], v2, s[2:3]
	v_add_u32_e32 v2, 0x2000, v2
	global_load_dwordx4 v[4:7], v2, s[2:3]
	v_add_u32_e32 v2, 0x2000, v2
	global_load_dwordx4 v[4:7], v2, s[2:3]
	v_add_u32_e32 v2, 0x2000, v2
	global_load_dwordx4 v[4:7], v2, s[2:3]
	v_add_u32_e32 v2, 0x2000, v2
	global_load_dwordx4 v[4:7], v2, s[2:3]
	v_add_u32_e32 v2, 0x2000, v2
	global_load_dwordx4 v[4:7], v2, s[2:3]
	v_add_u32_e32 v2, 0x2000, v2
	global_load_dwordx4 v[4:7], v2, s[2:3]
	v_add_u32_e32 v2, 0x2000, v2
	global_load_dwordx4 v[4:7], v2, s[2:3]
	v_add_u32_e32 v2, 0x2000, v2
	global_load_dwordx4 v[4:7], v2, s[2:3]
	v_add_u32_e32 v2, 0x2000, v2
	global_load_dwordx4 v[4:7], v2, s[2:3]
	v_add_u32_e32 v2, 0x2000, v2
	global_load_dwordx4 v[4:7], v2, s[2:3]
	v_add_u32_e32 v2, 0x2000, v2
	global_load_dwordx4 v[4:7], v2, s[2:3]
	v_add_u32_e32 v2, 0x2000, v2
	global_load_dwordx4 v[4:7], v2, s[2:3]
	v_add_u32_e32 v2, 0x2000, v2
	global_load_dwordx4 v[4:7], v2, s[2:3]
	v_add_u32_e32 v2, 0x2000, v2
	s_waitcnt vmcnt(0)
	s_branch .LBB0_181
